# sample conv unit: the z image is zeroed while the LDS-DMA copy of the filters is in flight (no vmcnt(0) after the copy; older loads waited with vmcnt(8))
# baseline (speedup 1.0000x reference)
.Lpf_copy:
	v_readfirstlane_b32 s12, v153
	v_and_b32_e32 v2, 63, v1
	s_lshl_b32 s10, s79, 14
	s_lshl_b32 s11, s12, 10
	s_add_i32 s10, s10, s11
	s_add_u32 s14, s66, 0x9c00000
	s_addc_u32 s15, s67, 0
	s_add_u32 s14, s14, s10
	s_addc_u32 s15, s15, 0
	s_add_i32 m0, s11, 0
	v_lshlrev_b32_e32 v2, 4, v2
	global_load_lds_dwordx4 v2, s[14:15]
	s_add_i32 m0, m0, 0x2000
	s_add_u32 s14, s14, 0x2000
	s_addc_u32 s15, s15, 0
	global_load_lds_dwordx4 v2, s[14:15]
	s_add_i32 m0, m0, 0x2000
	s_add_u32 s14, s14, 0x2000
	s_addc_u32 s15, s15, 0
	global_load_lds_dwordx4 v2, s[14:15]
	s_add_i32 m0, m0, 0x2000
	s_add_u32 s14, s14, 0x2000
	s_addc_u32 s15, s15, 0
	global_load_lds_dwordx4 v2, s[14:15]
	s_add_i32 m0, m0, 0x2000
	s_add_u32 s14, s14, 0x2000
	s_addc_u32 s15, s15, 0
	global_load_lds_dwordx4 v2, s[14:15]
	s_add_i32 m0, m0, 0x2000
	s_add_u32 s14, s14, 0x2000
	s_addc_u32 s15, s15, 0
	global_load_lds_dwordx4 v2, s[14:15]
	s_add_i32 m0, m0, 0x2000
	s_add_u32 s14, s14, 0x2000
	s_addc_u32 s15, s15, 0
	global_load_lds_dwordx4 v2, s[14:15]
	s_add_i32 m0, m0, 0x2000
	s_add_u32 s14, s14, 0x2000
	s_addc_u32 s15, s15, 0
	global_load_lds_dwordx4 v2, s[14:15]
	s_and_b64 s[10:11], s[30:31], exec
	s_cselect_b32 s85, s77, 0x5740
	s_lshr_b32 s12, s85, 2
	s_waitcnt vmcnt(8)
	s_branch .Lpf_nowait

.Lpf_nowait:
	v_add_u32_e32 v2, s36, v167
	s_mov_b64 s[10:11], 0
	v_mov_b32_e32 v3, v1
	s_waitcnt lgkmcnt(0)
	s_barrier
